# P3 chunk deltas: K-tile staging loop unrolled, 4 loads in flight (was one load per trip behind vmcnt(0))
# speedup vs baseline: 1.0004x; 1.0004x over previous
; #define LAS __attribute__((address_space(3)))
; template <int MASK> __device__ __forceinline__ void phase3(const Args& a, LAS unsigned char* lds, int tid, int wave, int lane, int vcu, int G) {
;     ...
;             for (int x = tid; x < 128 * 16; x += NTHREADS) { const int row = x >> 4, ch = x & 15;
;                 *(LAS u32x4*)(LK + row * 272 + 16 * ch) = *(const u32x4*)(P1 + ((size_t)128 * c + row) * P1W + C_MK + hd * 128 + 8 * ch); }
;             if (wave == 0) {
;                 const int t = 128 * c + 2 * lane;
;                 const float lf0 = LF[(size_t)t * 4 + hd], lf1 = LF[(size_t)(t + 1) * 4 + hd], ig0 = IG[(size_t)t * 4 + hd], ig1 = IG[(size_t)(t + 1) * 4 + hd];
;                 float S = lf0 + lf1;
; #pragma unroll
;                 for (int o = 1; o < 64; o <<= 1) { const float n = __shfl_up(S, o); if (lane >= o) S += n; }
;                 const float F1 = S, F0 = S - lf1, b0 = ig0 - F0, b1 = ig1 - F1;
;                 float Mx = fmaxf(b0, b1);
; #pragma unroll
;                 for (int o = 1; o < 64; o <<= 1) { const float n = __shfl_up(Mx, o); if (lane >= o) Mx = fmaxf(Mx, n); }
;                 float Mp = __shfl_up(Mx, 1); if (lane == 0) Mp = -INFINITY;
;                 const float cm0 = fmaxf(Mp, b0), cm1 = Mx;
;                 const float FL = __shfl(S, 63), cmL = __shfl(Mx, 63);
;                 BS[(size_t)t * 4 + hd] = b0; BS[(size_t)(t + 1) * 4 + hd] = b1; CMB[(size_t)t * 4 + hd] = cm0; CMB[(size_t)(t + 1) * 4 + hd] = cm1;
;                 if (lane == 0) { CH[c * 4 + hd] = FL; CH[1024 + c * 4 + hd] = cmL; }
;                 wl[2 * lane] = __expf(b0 - cmL); wl[2 * lane + 1] = __expf(b1 - cmL);
.LBB0_628:
	global_load_dwordx4 v[6:9], v[2:3], off
	s_mov_b64 s[2:3], 0x28000
	v_lshl_add_u64 v[10:11], v[2:3], 0, s[2:3]
	global_load_dwordx4 v[12:15], v[10:11], off
	v_lshl_add_u64 v[10:11], v[10:11], 0, s[2:3]
	global_load_dwordx4 v[16:19], v[10:11], off
	v_lshl_add_u64 v[10:11], v[10:11], 0, s[2:3]
	global_load_dwordx4 v[20:23], v[10:11], off
	s_waitcnt vmcnt(3)
	ds_write_b128 v1, v[6:9]
	s_waitcnt vmcnt(2)
	ds_write_b128 v1, v[12:15] offset:8704
	s_waitcnt vmcnt(1)
	ds_write_b128 v1, v[16:19] offset:17408
	s_waitcnt vmcnt(0)
	ds_write_b128 v1, v[20:23] offset:26112
	s_or_b64 exec, exec, s[48:49]
	s_and_b32 s49, s88, 3
	s_lshl_b32 s48, s52, 7
	s_and_b64 vcc, exec, s[82:83]
	s_cbranch_vccz .LBB0_633
	v_or_b32_e32 v4, s48, v209
	v_ashrrev_i32_e32 v5, 31, v4
	v_lshlrev_b64 v[2:3], 4, v[4:5]
	v_or_b32_e32 v4, 1, v4
	s_lshl_b32 s2, s49, 2
	v_ashrrev_i32_e32 v5, 31, v4
	v_or_b32_e32 v2, s2, v2
	v_lshlrev_b64 v[4:5], 4, v[4:5]
	v_lshl_add_u64 v[6:7], s[78:79], 0, v[2:3]
	v_or_b32_e32 v4, s2, v4
	global_load_dword v1, v[6:7], off
	v_lshl_add_u64 v[6:7], s[78:79], 0, v[4:5]
	global_load_dword v8, v[6:7], off
	v_lshl_add_u64 v[6:7], s[74:75], 0, v[2:3]
	global_load_dword v9, v[6:7], off
	v_lshl_add_u64 v[6:7], s[74:75], 0, v[4:5]
	global_load_dword v6, v[6:7], off
	v_and_b32_e32 v7, 64, v231
	v_add_u32_e32 v10, -1, v231
	v_cmp_lt_i32_e32 vcc, v10, v7
	v_readlane_b32 s8, v254, 52
	v_readlane_b32 s9, v254, 53
	v_cndmask_b32_e32 v10, v10, v231, vcc
	v_lshlrev_b32_e32 v10, 2, v10
	v_readlane_b32 s20, v254, 54
	v_readlane_b32 s21, v254, 55
	v_readlane_b32 s22, v254, 56
	v_readlane_b32 s23, v254, 57
	v_readlane_b32 s2, v254, 11
	v_readlane_b32 s3, v254, 12
	v_readlane_b32 s54, v254, 58
	v_readlane_b32 s55, v254, 59
	s_waitcnt vmcnt(2)
	v_add_f32_e32 v1, v1, v8
	ds_bpermute_b32 v11, v10, v1
	s_waitcnt lgkmcnt(0)
	v_add_f32_e32 v11, v1, v11
	v_cndmask_b32_e64 v1, v11, v1, s[0:1]
	v_add_u32_e32 v11, -2, v231
	v_cmp_lt_i32_e32 vcc, v11, v7
	s_nop 1
	v_cndmask_b32_e32 v11, v11, v231, vcc
	v_lshlrev_b32_e32 v11, 2, v11
	ds_bpermute_b32 v12, v11, v1
	s_waitcnt lgkmcnt(0)
	v_add_f32_e32 v12, v1, v12
	v_cndmask_b32_e64 v1, v12, v1, s[8:9]
	v_add_u32_e32 v12, -4, v231
	v_cmp_lt_i32_e32 vcc, v12, v7
	s_nop 1
	v_cndmask_b32_e32 v12, v12, v231, vcc
	v_lshlrev_b32_e32 v12, 2, v12
	ds_bpermute_b32 v13, v12, v1
	s_waitcnt lgkmcnt(0)
	v_add_f32_e32 v13, v1, v13
	v_cndmask_b32_e64 v1, v13, v1, s[20:21]
	v_add_u32_e32 v13, -8, v231
	v_cmp_lt_i32_e32 vcc, v13, v7
	s_nop 1
	v_cndmask_b32_e32 v13, v13, v231, vcc
	v_lshlrev_b32_e32 v13, 2, v13
	ds_bpermute_b32 v14, v13, v1
	s_waitcnt lgkmcnt(0)
	v_add_f32_e32 v14, v1, v14
	v_cndmask_b32_e64 v1, v14, v1, s[22:23]
	v_add_u32_e32 v14, -16, v231
	v_cmp_lt_i32_e32 vcc, v14, v7
	s_nop 1
	v_cndmask_b32_e32 v14, v14, v231, vcc
	v_lshlrev_b32_e32 v14, 2, v14
	ds_bpermute_b32 v15, v14, v1
	s_waitcnt lgkmcnt(0)
	v_add_f32_e32 v15, v1, v15
	v_cndmask_b32_e64 v1, v15, v1, s[2:3]
	v_subrev_u32_e32 v15, 32, v231
	v_cmp_lt_i32_e32 vcc, v15, v7
	s_nop 1
	v_cndmask_b32_e32 v7, v15, v231, vcc
	v_lshlrev_b32_e32 v7, 2, v7
	ds_bpermute_b32 v15, v7, v1
	s_waitcnt lgkmcnt(0)
	v_add_f32_e32 v15, v1, v15
	v_cndmask_b32_e64 v15, v15, v1, s[54:55]
	v_sub_f32_e32 v1, v15, v8
	s_waitcnt vmcnt(1)
	v_sub_f32_e32 v1, v9, v1
	s_waitcnt vmcnt(0)
	v_sub_f32_e32 v6, v6, v15
	v_max_f32_e32 v8, v1, v6
	ds_bpermute_b32 v9, v10, v8
	s_waitcnt lgkmcnt(0)
	v_max_f32_e32 v9, v9, v9
	v_max_f32_e32 v9, v8, v9
	v_cndmask_b32_e64 v8, v9, v8, s[0:1]
	ds_bpermute_b32 v9, v11, v8
	s_waitcnt lgkmcnt(0)
	v_max_f32_e32 v9, v9, v9
	v_max_f32_e32 v9, v8, v9
	v_cndmask_b32_e64 v8, v9, v8, s[8:9]
	ds_bpermute_b32 v9, v12, v8
	s_waitcnt lgkmcnt(0)
	v_max_f32_e32 v9, v9, v9
	v_max_f32_e32 v9, v8, v9
	v_cndmask_b32_e64 v8, v9, v8, s[20:21]
	ds_bpermute_b32 v9, v13, v8
	s_waitcnt lgkmcnt(0)
	v_max_f32_e32 v9, v9, v9
	v_max_f32_e32 v9, v8, v9
	v_cndmask_b32_e64 v8, v9, v8, s[22:23]
	ds_bpermute_b32 v9, v14, v8
	s_waitcnt lgkmcnt(0)
	v_max_f32_e32 v9, v9, v9
	v_max_f32_e32 v9, v8, v9
	v_cndmask_b32_e64 v8, v9, v8, s[2:3]
	ds_bpermute_b32 v7, v7, v8
	v_max_f32_e32 v9, v8, v8
	v_readlane_b32 s2, v253, 63
	v_readlane_b32 s3, v254, 0
	s_waitcnt lgkmcnt(0)
	v_max_f32_e32 v7, v7, v7
	v_max_f32_e32 v7, v9, v7
	v_cndmask_b32_e64 v9, v7, v8, s[54:55]
	ds_bpermute_b32 v7, v10, v9
	ds_bpermute_b32 v8, v233, v15
	v_lshl_add_u64 v[10:11], s[2:3], 0, v[2:3]
	global_store_dword v[10:11], v1, off
	v_lshl_add_u64 v[10:11], s[2:3], 0, v[4:5]
	s_waitcnt lgkmcnt(1)
	v_cndmask_b32_e64 v7, v7, v232, s[0:1]
	v_max_f32_e32 v7, v7, v7
	v_max_f32_e32 v12, v7, v1
	ds_bpermute_b32 v7, v233, v9
	v_readlane_b32 s2, v254, 1
	v_readlane_b32 s3, v254, 2
	global_store_dword v[10:11], v6, off
	s_nop 0
	v_lshl_add_u64 v[2:3], s[2:3], 0, v[2:3]
	global_store_dword v[2:3], v12, off
	v_lshl_add_u64 v[2:3], s[2:3], 0, v[4:5]
	global_store_dword v[2:3], v9, off
	s_and_saveexec_b64 s[54:55], s[0:1]
	s_cbranch_execz .LBB0_632
	s_ashr_i32 s89, s88, 31
	s_lshl_b64 s[2:3], s[88:89], 2
	v_readlane_b32 s4, v254, 3
	s_add_u32 s2, s4, s2
	v_readlane_b32 s8, v254, 4
	s_addc_u32 s3, s8, s3
	s_and_b32 s52, s88, -4
	s_or_b32 s52, s52, s49
	s_add_i32 s68, s52, 0x400
	s_ashr_i32 s69, s68, 31
	s_lshl_b64 s[68:69], s[68:69], 2
	s_add_u32 s68, s4, s68
	s_addc_u32 s69, s8, s69
	s_waitcnt lgkmcnt(1)
	global_store_dword v95, v8, s[2:3]
	s_waitcnt lgkmcnt(0)
	global_store_dword v95, v7, s[68:69]
	s_mov_b32 s68, s66
